# v_c11 + attention KV loop: the 8 in-place canonicalizing v_max_f32 x,x,x on the row-max chain removed (identity under IEEE mode with denormals preserved)
# baseline (speedup 1.0000x reference)
; __device__ __forceinline__ float xor16_max(float v) { const auto r = __builtin_amdgcn_permlane16_swap(__float_as_uint(v), __float_as_uint(v), false, false); return fmaxf(__uint_as_float(r[0]), __uint_as_float(r[1])); }
; __device__ __forceinline__ float xor32_max(float v) { const auto r = __builtin_amdgcn_permlane32_swap(__float_as_uint(v), __float_as_uint(v), false, false); return fmaxf(__uint_as_float(r[0]), __uint_as_float(r[1])); }
; #define ATT_LDK(dst_, t16_) do { _Pragma("unroll") for (int sk = 0; sk < 4; ++sk) dst_[sk] = *(const LAS bf16x8*)(kb_ + (16 * (t16_) + l15) * 272 + (32 * sk + 8 * q4) * 2); } while (0)
; #define ATT_QK(src_, t16_) do { f32x4 acc = (f32x4){0.f, 0.f, 0.f, 0.f}; _Pragma("unroll") for (int sk = 0; sk < 4; ++sk) acc = mfma16(src_[sk], qf[sk], acc); s[t16_] = acc; } while (0)
; #define ATT_SB() __builtin_amdgcn_sched_barrier(0)
; __device__ __forceinline__ void attn_phase(LAS unsigned char* lds, const bf16* PROJ, bf16* MIX, const float* lq1, const float* lk1, const float* lq2, const float* lk2,
;                                            const float* norm_g, float lambda_init, int G, int wave_s) {
;     ...
;                   ATT_LDK(kfa, 0); ATT_LDK(kfb, 1); ATT_SB(); ATT_QK(kfa, 0); ATT_LDK(kfa, 2); ATT_SB(); ATT_QK(kfb, 1); ATT_LDK(kfb, 3); ATT_SB(); ATT_QK(kfa, 2); ATT_QK(kfb, 3); }
;                 const int dq = 64 * kt + qloc; const bool diag = (kt == 0);
;                 const float nb = -sl2 * ((float)dq - q4f);
;                 float mx = -1e30f;
; #pragma unroll
;                 for (int t16 = 0; t16 < 4; ++t16)
; #pragma unroll
;                     for (int r = 0; r < 4; ++r) { const int kl = 16 * t16 + 4 * q4 + r; float v = fmaf(s[t16][r], c1, fmaf(sl2, (float)(16 * t16 + r), nb));
;                         if (diag && kl > qloc) v = -1e30f; s[t16][r] = v; mx = fmaxf(mx, v); }
;                 mx = xor32_max(xor16_max(mx));
;                 const bool resc = __builtin_amdgcn_ballot_w64(mx > m_run) != 0ull;
;                 const float mn = fmaxf(m_run, mx), alpha = __builtin_amdgcn_exp2f(m_run - mn); m_run = mn;
.LBB0_892:
	ds_read_b128 v[114:117], v209
	ds_read_b128 v[118:121], v209 offset:64
	ds_read_b128 v[122:125], v209 offset:128
	ds_read_b128 v[126:129], v209 offset:192
	ds_read_b128 v[130:133], v209 offset:4352
	ds_read_b128 v[134:137], v209 offset:4416
	ds_read_b128 v[228:231], v209 offset:4480
	ds_read_b128 v[232:235], v209 offset:4544
	s_waitcnt lgkmcnt(7)
	v_mfma_f32_16x16x32_bf16 v[114:117], v[114:117], v[74:77], 0
	s_waitcnt lgkmcnt(6)
	v_mfma_f32_16x16x32_bf16 v[114:117], v[118:121], v[66:69], v[114:117]
	s_waitcnt lgkmcnt(5)
	v_mfma_f32_16x16x32_bf16 v[114:117], v[122:125], v[70:73], v[114:117]
	s_waitcnt lgkmcnt(4)
	v_mfma_f32_16x16x32_bf16 v[114:117], v[126:129], v[78:81], v[114:117]
	ds_read_b128 v[118:121], v209 offset:8704
	ds_read_b128 v[122:125], v209 offset:8768
	ds_read_b128 v[126:129], v209 offset:8832
	ds_read_b128 v[236:239], v209 offset:8896
	s_waitcnt lgkmcnt(7)
	v_mfma_f32_16x16x32_bf16 v[130:133], v[130:133], v[74:77], 0
	s_waitcnt lgkmcnt(6)
	v_mfma_f32_16x16x32_bf16 v[130:133], v[134:137], v[66:69], v[130:133]
	s_waitcnt lgkmcnt(5)
	v_mfma_f32_16x16x32_bf16 v[130:133], v[228:231], v[70:73], v[130:133]
	s_waitcnt lgkmcnt(4)
	v_mfma_f32_16x16x32_bf16 v[134:137], v[232:235], v[78:81], v[130:133]
	s_nop 5
	ds_read_b128 v[130:133], v209 offset:13056
	ds_read_b128 v[228:231], v209 offset:13120
	ds_read_b128 v[232:235], v209 offset:13184
	ds_read_b128 v[240:243], v209 offset:13248
	s_waitcnt lgkmcnt(7)
	v_mfma_f32_16x16x32_bf16 v[118:121], v[118:121], v[74:77], 0
	v_cvt_f32_u32_e32 v0, v224
	s_cmp_eq_u32 s88, 0
	s_cselect_b64 s[26:27], -1, 0
	s_waitcnt lgkmcnt(6)
	v_mfma_f32_16x16x32_bf16 v[118:121], v[122:125], v[66:69], v[118:121]
	v_sub_f32_e32 v0, v0, v166
	s_and_b64 vcc, s[26:27], s[40:41]
	s_waitcnt lgkmcnt(5)
	v_mfma_f32_16x16x32_bf16 v[118:121], v[126:129], v[70:73], v[118:121]
	v_mul_f32_e64 v126, v0, -v211
	v_fma_f32 v127, 0, v211, v126
	v_fmac_f32_e32 v127, 0x3e0293ee, v114
	v_fma_f32 v0, v0, -v211, v211
	s_waitcnt lgkmcnt(3)
	v_mfma_f32_16x16x32_bf16 v[122:125], v[130:133], v[74:77], 0
	v_cndmask_b32_e32 v130, v127, v219, vcc
	v_fmac_f32_e32 v0, 0x3e0293ee, v115
	s_and_b64 vcc, s[26:27], s[42:43]
	v_fma_f32 v114, 2.0, v211, v126
	v_cndmask_b32_e32 v131, v0, v219, vcc
	v_fmac_f32_e32 v114, 0x3e0293ee, v116
	s_and_b64 vcc, s[26:27], s[44:45]
	v_cndmask_b32_e32 v132, v114, v219, vcc
	v_fmamk_f32 v114, v211, 0x40400000, v126
	v_fmac_f32_e32 v114, 0x3e0293ee, v117
	s_and_b64 vcc, s[26:27], s[46:47]
	v_cndmask_b32_e32 v133, v114, v219, vcc
	v_fmamk_f32 v114, v211, 0x41800000, v126
	v_fmac_f32_e32 v114, 0x3e0293ee, v134
	s_and_b64 vcc, s[26:27], s[48:49]
	v_cndmask_b32_e32 v134, v114, v219, vcc
	v_fmamk_f32 v114, v211, 0x41880000, v126
	v_fmac_f32_e32 v114, 0x3e0293ee, v135
	s_and_b64 vcc, s[26:27], s[50:51]
	v_cndmask_b32_e32 v135, v114, v219, vcc
	v_fmamk_f32 v114, v211, 0x41900000, v126
	v_mfma_f32_16x16x32_bf16 v[118:121], v[236:239], v[78:81], v[118:121]
	v_fmac_f32_e32 v114, 0x3e0293ee, v136
	s_and_b64 vcc, s[26:27], s[52:53]
	v_cndmask_b32_e32 v136, v114, v219, vcc
	s_waitcnt lgkmcnt(2)
	v_mfma_f32_16x16x32_bf16 v[122:125], v[228:231], v[66:69], v[122:125]
	v_fmamk_f32 v114, v211, 0x41980000, v126
	v_fmac_f32_e32 v114, 0x3e0293ee, v137
	s_and_b64 vcc, s[26:27], s[54:55]
	v_cndmask_b32_e32 v137, v114, v219, vcc
	v_fmamk_f32 v114, v211, 0x42000000, v126
	s_waitcnt lgkmcnt(1)
	v_mfma_f32_16x16x32_bf16 v[122:125], v[232:235], v[70:73], v[122:125]
	v_fmac_f32_e32 v114, 0x3e0293ee, v118
	s_and_b64 vcc, s[26:27], s[56:57]
	v_cndmask_b32_e32 v227, v114, v219, vcc
	v_fmamk_f32 v114, v211, 0x42040000, v126
	v_fmac_f32_e32 v114, 0x3e0293ee, v119
	s_and_b64 vcc, s[26:27], s[58:59]
	v_cndmask_b32_e32 v229, v114, v219, vcc
	v_fmamk_f32 v114, v211, 0x42080000, v126
	s_waitcnt lgkmcnt(0)
	v_mfma_f32_16x16x32_bf16 v[122:125], v[240:243], v[78:81], v[122:125]
	v_fmac_f32_e32 v114, 0x3e0293ee, v120
	s_and_b64 vcc, s[26:27], s[60:61]
	v_cndmask_b32_e32 v230, v114, v219, vcc
	v_fmamk_f32 v114, v211, 0x420c0000, v126
	v_fmac_f32_e32 v114, 0x3e0293ee, v121
	s_and_b64 vcc, s[26:27], s[62:63]
	v_cndmask_b32_e32 v231, v114, v219, vcc
	v_fmamk_f32 v114, v211, 0x42400000, v126
	v_max3_f32 v0, v130, s4, v131
	v_fmac_f32_e32 v114, 0x3e0293ee, v122
	s_and_b64 vcc, s[26:27], s[64:65]
	v_max3_f32 v0, v0, v132, v133
	v_cndmask_b32_e32 v232, v114, v219, vcc
	v_fmamk_f32 v114, v211, 0x42440000, v126
	v_max3_f32 v0, v0, v134, v135
	v_fmac_f32_e32 v114, 0x3e0293ee, v123
	s_and_b64 vcc, s[26:27], s[66:67]
	v_max3_f32 v0, v0, v136, v137
	v_cndmask_b32_e32 v233, v114, v219, vcc
	v_fmamk_f32 v114, v211, 0x42480000, v126
	v_max3_f32 v0, v0, v227, v229
	v_fmac_f32_e32 v114, 0x3e0293ee, v124
	s_and_b64 vcc, s[26:27], s[68:69]
	v_fmac_f32_e32 v126, 0x424c0000, v211
	v_max3_f32 v0, v0, v230, v231
	v_cndmask_b32_e32 v234, v114, v219, vcc
	v_fmac_f32_e32 v126, 0x3e0293ee, v125
	s_and_b64 vcc, s[26:27], s[70:71]
	v_max3_f32 v0, v0, v232, v233
	v_cndmask_b32_e32 v235, v126, v219, vcc
	v_max3_f32 v0, v0, v234, v235
	v_mov_b32_e32 v114, v0
	s_nop 1
	v_permlane16_swap_b32_e32 v0, v114
	v_max_f32_e32 v0, v0, v114
	v_mov_b32_e32 v114, v0
	s_nop 1
	v_permlane32_swap_b32_e32 v0, v114
	v_max_f32_e32 v0, v0, v114
	v_max_f32_e32 v114, v226, v226
	v_max_f32_e32 v228, v114, v0
	ds_read_b64_tr_b16 v[126:127], v162 offset:34816
	ds_read_b64_tr_b16 v[114:115], v162 offset:34848
	ds_read_b64_tr_b16 v[128:129], v162 offset:43520
	ds_read_b64_tr_b16 v[122:123], v162 offset:52224
	ds_read_b64_tr_b16 v[124:125], v162 offset:60928
	ds_read_b64_tr_b16 v[116:117], v162 offset:43552
	ds_read_b64_tr_b16 v[118:119], v162 offset:52256
	ds_read_b64_tr_b16 v[120:121], v162 offset:60960
	v_cmp_gt_f32_e32 vcc, v0, v226
	v_sub_f32_e32 v0, v226, v228
	v_exp_f32_e32 v0, v0
	s_cbranch_vccz .LBB0_894
; __device__ __forceinline__ void attn_phase(LAS unsigned char* lds, const bf16* PROJ, bf16* MIX, const float* lq1, const float* lk1, const float* lq2, const float* lk2,
;                                            const float* norm_g, float lambda_init, int G, int wave_s) {
;     ...
;                   if (resc) {
; #pragma unroll
;                   for (int mt = 0; mt < 16; ++mt) O[mt] = O[mt] * alpha; }
	v_pk_mul_f32 v[64:65], v[64:65], v[0:1] op_sel_hi:[1,0]
	v_pk_mul_f32 v[62:63], v[62:63], v[0:1] op_sel_hi:[1,0]
	v_pk_mul_f32 v[60:61], v[60:61], v[0:1] op_sel_hi:[1,0]
	v_pk_mul_f32 v[58:59], v[58:59], v[0:1] op_sel_hi:[1,0]
	v_pk_mul_f32 v[56:57], v[56:57], v[0:1] op_sel_hi:[1,0]
	v_pk_mul_f32 v[54:55], v[54:55], v[0:1] op_sel_hi:[1,0]
	v_pk_mul_f32 v[52:53], v[52:53], v[0:1] op_sel_hi:[1,0]
	v_pk_mul_f32 v[50:51], v[50:51], v[0:1] op_sel_hi:[1,0]
	v_pk_mul_f32 v[48:49], v[48:49], v[0:1] op_sel_hi:[1,0]
	v_pk_mul_f32 v[46:47], v[46:47], v[0:1] op_sel_hi:[1,0]
	v_pk_mul_f32 v[44:45], v[44:45], v[0:1] op_sel_hi:[1,0]
	v_pk_mul_f32 v[42:43], v[42:43], v[0:1] op_sel_hi:[1,0]
	v_pk_mul_f32 v[40:41], v[40:41], v[0:1] op_sel_hi:[1,0]
	v_pk_mul_f32 v[38:39], v[38:39], v[0:1] op_sel_hi:[1,0]
	v_pk_mul_f32 v[36:37], v[36:37], v[0:1] op_sel_hi:[1,0]
	v_pk_mul_f32 v[34:35], v[34:35], v[0:1] op_sel_hi:[1,0]
	v_pk_mul_f32 v[32:33], v[32:33], v[0:1] op_sel_hi:[1,0]
	v_pk_mul_f32 v[30:31], v[30:31], v[0:1] op_sel_hi:[1,0]
	v_pk_mul_f32 v[28:29], v[28:29], v[0:1] op_sel_hi:[1,0]
	v_pk_mul_f32 v[26:27], v[26:27], v[0:1] op_sel_hi:[1,0]
	v_pk_mul_f32 v[24:25], v[24:25], v[0:1] op_sel_hi:[1,0]
	v_pk_mul_f32 v[22:23], v[22:23], v[0:1] op_sel_hi:[1,0]
	v_pk_mul_f32 v[16:17], v[16:17], v[0:1] op_sel_hi:[1,0]
	v_pk_mul_f32 v[14:15], v[14:15], v[0:1] op_sel_hi:[1,0]
	v_pk_mul_f32 v[20:21], v[20:21], v[0:1] op_sel_hi:[1,0]
	v_pk_mul_f32 v[18:19], v[18:19], v[0:1] op_sel_hi:[1,0]
	v_pk_mul_f32 v[12:13], v[12:13], v[0:1] op_sel_hi:[1,0]
	v_pk_mul_f32 v[10:11], v[10:11], v[0:1] op_sel_hi:[1,0]
	v_pk_mul_f32 v[8:9], v[8:9], v[0:1] op_sel_hi:[1,0]
	v_pk_mul_f32 v[6:7], v[6:7], v[0:1] op_sel_hi:[1,0]
	v_pk_mul_f32 v[4:5], v[4:5], v[0:1] op_sel_hi:[1,0]
	v_pk_mul_f32 v[2:3], v[2:3], v[0:1] op_sel_hi:[1,0]

; __device__ __forceinline__ float xor16_max(float v) { const auto r = __builtin_amdgcn_permlane16_swap(__float_as_uint(v), __float_as_uint(v), false, false); return fmaxf(__uint_as_float(r[0]), __uint_as_float(r[1])); }
; __device__ __forceinline__ void attn_phase(LAS unsigned char* lds, const bf16* PROJ, bf16* MIX, const float* lq1, const float* lk1, const float* lq2, const float* lk2,
;                                            const float* norm_g, float lambda_init, int G, int wave_s) {
;     ...
;                 { bf16x8 kfa[4], kfb[4];
;                   ATT_LDK(kfa, 0); ATT_LDK(kfb, 1); ATT_SB(); ATT_QK(kfa, 0); ATT_LDK(kfa, 2); ATT_SB(); ATT_QK(kfb, 1); ATT_LDK(kfb, 3); ATT_SB(); ATT_QK(kfa, 2); ATT_QK(kfb, 3); }
;                 const int dq = 64 * kt + qloc; const bool diag = (kt == 0);
;                 const float nb = -sl2 * ((float)dq - q4f);
;                 float mx = -1e30f;
; #pragma unroll
;                 for (int t16 = 0; t16 < 4; ++t16)
; #pragma unroll
;                     for (int r = 0; r < 4; ++r) { const int kl = 16 * t16 + 4 * q4 + r; float v = fmaf(s[t16][r], c1, fmaf(sl2, (float)(16 * t16 + r), nb));
;                         if (diag && kl > qloc) v = -1e30f; s[t16][r] = v; mx = fmaxf(mx, v); }
;                 mx = xor32_max(xor16_max(mx));
;                 const bool resc = __builtin_amdgcn_ballot_w64(mx > m_run) != 0ull;
;                 const float mn = fmaxf(m_run, mx), alpha = __builtin_amdgcn_exp2f(m_run - mn); m_run = mn;
;                 float ps = 0.f;
; #pragma unroll
;                 for (int t16 = 0; t16 < 4; ++t16)
; #pragma unroll
;                     for (int r = 0; r < 4; ++r) { const float pv = __builtin_amdgcn_exp2f(s[t16][r] - mn); s[t16][r] = pv; ps += pv; }
;                 l_part = l_part * alpha + ps;
;                 bf16x8 pf[2];
; #pragma unroll
;                 for (int ks = 0; ks < 2; ++ks) { v4u pw; pw.x = pk2(s[2 * ks][0], s[2 * ks][1]); pw.y = pk2(s[2 * ks][2], s[2 * ks][3]); pw.z = pk2(s[2 * ks + 1][0], s[2 * ks + 1][1]); pw.w = pk2(s[2 * ks + 1][2], s[2 * ks + 1][3]);
;                     pf[ks] = __builtin_bit_cast(bf16x8, pw); }
;                 { bf16x8 va[2], vb[2], vc[2];
;                   ATT_LDV(va, 0); ATT_LDV(vb, 1);
;                   if (resc) {
; #pragma unroll
;                   for (int mt = 0; mt < 16; ++mt) O[mt] = O[mt] * alpha; }
.LBB0_898:
	ds_read_b128 v[114:117], v210
	ds_read_b128 v[118:121], v210 offset:64
	ds_read_b128 v[122:125], v210 offset:128
	ds_read_b128 v[126:129], v210 offset:192
	ds_read_b128 v[130:133], v210 offset:4352
	ds_read_b128 v[134:137], v210 offset:4416
	ds_read_b128 v[230:233], v210 offset:4480
	ds_read_b128 v[234:237], v210 offset:4544
	s_waitcnt lgkmcnt(7)
	v_mfma_f32_16x16x32_bf16 v[114:117], v[114:117], v[74:77], 0
	s_waitcnt lgkmcnt(6)
	v_mfma_f32_16x16x32_bf16 v[114:117], v[118:121], v[66:69], v[114:117]
	s_waitcnt lgkmcnt(5)
	v_mfma_f32_16x16x32_bf16 v[114:117], v[122:125], v[70:73], v[114:117]
	s_waitcnt lgkmcnt(4)
	v_mfma_f32_16x16x32_bf16 v[116:119], v[126:129], v[78:81], v[114:117]
	ds_read_b128 v[120:123], v210 offset:8704
	ds_read_b128 v[124:127], v210 offset:8768
	ds_read_b128 v[238:241], v210 offset:8832
	ds_read_b128 v[242:245], v210 offset:8896
	s_waitcnt lgkmcnt(7)
	v_mfma_f32_16x16x32_bf16 v[128:131], v[130:133], v[74:77], 0
	s_waitcnt lgkmcnt(6)
	v_mfma_f32_16x16x32_bf16 v[128:131], v[134:137], v[66:69], v[128:131]
	s_waitcnt lgkmcnt(5)
	v_mfma_f32_16x16x32_bf16 v[128:131], v[230:233], v[70:73], v[128:131]
	s_waitcnt lgkmcnt(4)
	v_mfma_f32_16x16x32_bf16 v[128:131], v[234:237], v[78:81], v[128:131]
	ds_read_b128 v[132:135], v210 offset:13056
	ds_read_b128 v[230:233], v210 offset:13120
	ds_read_b128 v[234:237], v210 offset:13184
	ds_read_b128 v[246:249], v210 offset:13248
	s_waitcnt lgkmcnt(7)
	v_mfma_f32_16x16x32_bf16 v[120:123], v[120:123], v[74:77], 0
	v_add_u32_e32 v0, 64, v224
	v_cvt_f32_u32_e32 v0, v0
	v_sub_f32_e32 v0, v0, v166
	s_waitcnt lgkmcnt(3)
	v_mfma_f32_16x16x32_bf16 v[132:135], v[132:135], v[74:77], 0
	v_mul_f32_e64 v114, v0, -v211
	v_fma_f32 v115, 0, v211, v114
	v_fmac_f32_e32 v115, 0x3e0293ee, v116
	v_mfma_f32_16x16x32_bf16 v[120:123], v[124:127], v[66:69], v[120:123]
	v_fma_f32 v116, v0, -v211, v211
	v_fmac_f32_e32 v116, 0x3e0293ee, v117
	v_fma_f32 v117, 2.0, v211, v114
	s_waitcnt lgkmcnt(2)
	v_mfma_f32_16x16x32_bf16 v[132:135], v[230:233], v[66:69], v[132:135]
	v_fmac_f32_e32 v117, 0x3e0293ee, v118
	v_fmamk_f32 v118, v211, 0x40400000, v114
	v_max3_f32 v0, v115, s4, v116
	v_mfma_f32_16x16x32_bf16 v[120:123], v[238:241], v[70:73], v[120:123]
	v_fmac_f32_e32 v118, 0x3e0293ee, v119
	v_fmamk_f32 v119, v211, 0x41800000, v114
	v_max3_f32 v0, v0, v117, v118
	s_waitcnt lgkmcnt(1)
	v_mfma_f32_16x16x32_bf16 v[132:135], v[234:237], v[70:73], v[132:135]
	v_fmac_f32_e32 v119, 0x3e0293ee, v128
	v_fmamk_f32 v225, v211, 0x41980000, v114
	v_fmac_f32_e32 v225, 0x3e0293ee, v131
	v_mfma_f32_16x16x32_bf16 v[122:125], v[242:245], v[78:81], v[120:123]
	v_fmamk_f32 v230, v211, 0x42000000, v114
	v_fmamk_f32 v231, v211, 0x42040000, v114
	v_fmamk_f32 v233, v211, 0x42080000, v114
	v_fmamk_f32 v120, v211, 0x41880000, v114
	s_waitcnt lgkmcnt(0)
	v_mfma_f32_16x16x32_bf16 v[132:135], v[246:249], v[78:81], v[132:135]
	v_fmac_f32_e32 v120, 0x3e0293ee, v129
	v_fmamk_f32 v121, v211, 0x41900000, v114
	v_max3_f32 v0, v0, v119, v120
	v_fmac_f32_e32 v121, 0x3e0293ee, v130
	v_max3_f32 v0, v0, v121, v225
	v_fmac_f32_e32 v230, 0x3e0293ee, v122
	v_fmac_f32_e32 v231, 0x3e0293ee, v123
	v_fmamk_f32 v234, v211, 0x420c0000, v114
	v_max3_f32 v0, v0, v230, v231
	v_fmac_f32_e32 v233, 0x3e0293ee, v124
	v_fmac_f32_e32 v234, 0x3e0293ee, v125
	v_fmamk_f32 v229, v211, 0x42400000, v114
	v_fmamk_f32 v232, v211, 0x42440000, v114
	v_max3_f32 v0, v0, v233, v234
	v_fmac_f32_e32 v229, 0x3e0293ee, v132
	v_fmac_f32_e32 v232, 0x3e0293ee, v133
	v_fmamk_f32 v235, v211, 0x42480000, v114
	v_fmac_f32_e32 v114, 0x424c0000, v211
	v_max3_f32 v0, v0, v229, v232
	v_fmac_f32_e32 v235, 0x3e0293ee, v134
	v_fmac_f32_e32 v114, 0x3e0293ee, v135
	v_max3_f32 v0, v0, v235, v114
	v_mov_b32_e32 v122, v0
	s_nop 1
	v_permlane16_swap_b32_e32 v0, v122
	v_max_f32_e32 v0, v0, v122
	v_mov_b32_e32 v122, v0
	s_nop 1
	v_permlane32_swap_b32_e32 v0, v122
	v_max_f32_e32 v0, v0, v122
	v_max_f32_e32 v122, v228, v228
	v_max_f32_e32 v226, v122, v0
	v_add_u32_e32 v122, 0x19800, v162
	v_add_u32_e32 v124, 0x1fe20, v162
	ds_read_b64_tr_b16 v[134:135], v122
	ds_read_b64_tr_b16 v[124:125], v124
	v_add_u32_e32 v122, 0x1ba00, v162
	ds_read_b64_tr_b16 v[136:137], v122
	v_add_u32_e32 v122, 0x1dc00, v162
	ds_read_b64_tr_b16 v[126:127], v122
	v_add_u32_e32 v122, 0x1fe00, v162
	ds_read_b64_tr_b16 v[128:129], v122
	v_add_u32_e32 v122, 0x19820, v162
	ds_read_b64_tr_b16 v[130:131], v122
	v_add_u32_e32 v122, 0x1ba20, v162
	ds_read_b64_tr_b16 v[132:133], v122
	v_add_u32_e32 v122, 0x1dc20, v162
	v_cmp_gt_f32_e32 vcc, v0, v228
	v_sub_f32_e32 v0, v228, v226
	ds_read_b64_tr_b16 v[122:123], v122
	v_exp_f32_e32 v0, v0
	s_cbranch_vccz .LBB0_900
	v_pk_mul_f32 v[64:65], v[64:65], v[0:1] op_sel_hi:[1,0]
	v_pk_mul_f32 v[62:63], v[62:63], v[0:1] op_sel_hi:[1,0]
	v_pk_mul_f32 v[60:61], v[60:61], v[0:1] op_sel_hi:[1,0]
	v_pk_mul_f32 v[58:59], v[58:59], v[0:1] op_sel_hi:[1,0]
	v_pk_mul_f32 v[56:57], v[56:57], v[0:1] op_sel_hi:[1,0]
	v_pk_mul_f32 v[54:55], v[54:55], v[0:1] op_sel_hi:[1,0]
	v_pk_mul_f32 v[52:53], v[52:53], v[0:1] op_sel_hi:[1,0]
	v_pk_mul_f32 v[50:51], v[50:51], v[0:1] op_sel_hi:[1,0]
	v_pk_mul_f32 v[48:49], v[48:49], v[0:1] op_sel_hi:[1,0]
	v_pk_mul_f32 v[46:47], v[46:47], v[0:1] op_sel_hi:[1,0]
	v_pk_mul_f32 v[44:45], v[44:45], v[0:1] op_sel_hi:[1,0]
	v_pk_mul_f32 v[42:43], v[42:43], v[0:1] op_sel_hi:[1,0]
	v_pk_mul_f32 v[40:41], v[40:41], v[0:1] op_sel_hi:[1,0]
	v_pk_mul_f32 v[38:39], v[38:39], v[0:1] op_sel_hi:[1,0]
	v_pk_mul_f32 v[36:37], v[36:37], v[0:1] op_sel_hi:[1,0]
	v_pk_mul_f32 v[34:35], v[34:35], v[0:1] op_sel_hi:[1,0]
	v_pk_mul_f32 v[32:33], v[32:33], v[0:1] op_sel_hi:[1,0]
	v_pk_mul_f32 v[30:31], v[30:31], v[0:1] op_sel_hi:[1,0]
	v_pk_mul_f32 v[28:29], v[28:29], v[0:1] op_sel_hi:[1,0]
	v_pk_mul_f32 v[26:27], v[26:27], v[0:1] op_sel_hi:[1,0]
	v_pk_mul_f32 v[24:25], v[24:25], v[0:1] op_sel_hi:[1,0]
	v_pk_mul_f32 v[22:23], v[22:23], v[0:1] op_sel_hi:[1,0]
	v_pk_mul_f32 v[16:17], v[16:17], v[0:1] op_sel_hi:[1,0]
	v_pk_mul_f32 v[14:15], v[14:15], v[0:1] op_sel_hi:[1,0]
	v_pk_mul_f32 v[20:21], v[20:21], v[0:1] op_sel_hi:[1,0]
	v_pk_mul_f32 v[18:19], v[18:19], v[0:1] op_sel_hi:[1,0]
	v_pk_mul_f32 v[12:13], v[12:13], v[0:1] op_sel_hi:[1,0]
	v_pk_mul_f32 v[10:11], v[10:11], v[0:1] op_sel_hi:[1,0]
	v_pk_mul_f32 v[8:9], v[8:9], v[0:1] op_sel_hi:[1,0]
	v_pk_mul_f32 v[6:7], v[6:7], v[0:1] op_sel_hi:[1,0]
	v_pk_mul_f32 v[4:5], v[4:5], v[0:1] op_sel_hi:[1,0]
	v_pk_mul_f32 v[2:3], v[2:3], v[0:1] op_sel_hi:[1,0]
